# hand-written NSA top-k rank selection (wide LDS reads, no per-block branches); MLA loop prefetch loads de-serialized
# speedup vs baseline: 1.0435x; 1.0048x over previous
.LBB0_1140:
	s_or_b64 exec, exec, s[2:3]
	v_mul_u32_u24_e32 v40, 0x110, v42
	v_add_u32_e32 v50, v48, v40
	s_waitcnt lgkmcnt(0)
	v_cvt_pk_bf16_f32 v35, v6, v7
	v_cvt_pk_bf16_f32 v37, v8, v9
	ds_read2_b64 v[6:9], v50 offset1:4
	v_cvt_pk_bf16_f32 v34, v0, v1
	v_cvt_pk_bf16_f32 v1, v2, v3
	v_cvt_pk_bf16_f32 v2, v10, v11
	v_cvt_pk_bf16_f32 v3, v12, v13
	ds_read2_b64 v[10:13], v50 offset0:8 offset1:12
	v_lshl_add_u64 v[160:161], v[154:155], 0, s[96:97]
	s_movk_i32 s2, 0xc0
	v_mad_u64_u32 v[18:19], s[0:1], v160, s2, v[18:19]
	v_cvt_pk_bf16_f32 v36, v38, v39
	v_add_u32_e32 v51, 0x1000, v50
	v_mad_i32_i24 v19, v161, s2, v19
	s_waitcnt lgkmcnt(1)
	v_mfma_f32_16x16x32_bf16 v[6:9], v[6:9], v[34:37], 0
	ds_read2_b64 v[38:41], v51 offset0:32 offset1:36
	global_load_dword v18, v[18:19], off
	v_cvt_pk_bf16_f32 v0, v4, v5
	v_add_u32_e32 v52, 0x2000, v50
	s_waitcnt lgkmcnt(0)
	v_mfma_f32_16x16x32_bf16 v[38:41], v[38:41], v[34:37], 0
	ds_read2_b64 v[42:45], v52 offset0:64 offset1:68
	v_add_u32_e32 v53, 0x3000, v50
	ds_read2_b64 v[46:49], v53 offset0:96 offset1:100
	v_mfma_f32_16x16x32_bf16 v[4:7], v[10:13], v[0:3], v[6:9]
	v_cvt_pk_bf16_f32 v12, v14, v15
	v_cvt_pk_bf16_f32 v13, v20, v21
	v_cvt_pk_bf16_f32 v14, v22, v23
	ds_read2_b64 v[8:11], v51 offset0:40 offset1:44
	s_waitcnt lgkmcnt(0)
	v_mfma_f32_16x16x32_bf16 v[8:11], v[8:11], v[0:3], v[38:41]
	s_nop 2
	ds_read2_b64 v[38:41], v52 offset0:72 offset1:76
	ds_read2_b64 v[20:23], v50 offset0:16 offset1:20
	v_cvt_pk_bf16_f32 v15, v24, v25
	v_mfma_f32_16x16x32_bf16 v[42:45], v[42:45], v[34:37], 0
	v_cvt_pk_bf16_f32 v24, v26, v27
	v_cvt_pk_bf16_f32 v25, v30, v31
	v_cvt_pk_bf16_f32 v26, v28, v29
	s_waitcnt lgkmcnt(1)
	v_mfma_f32_16x16x32_bf16 v[38:41], v[38:41], v[0:3], v[42:45]
	v_cvt_pk_bf16_f32 v27, v32, v33
	s_nop 1
	ds_read2_b64 v[42:45], v53 offset0:104 offset1:108
	v_lshlrev_b64 v[166:167], 12, v[160:161]
	s_waitcnt lgkmcnt(1)
	v_mfma_f32_16x16x32_bf16 v[4:7], v[20:23], v[12:15], v[4:7]
	ds_read2_b64 v[20:23], v51 offset0:48 offset1:52
	v_lshl_add_u64 v[16:17], v[16:17], 0, v[166:167]
	v_mfma_f32_16x16x32_bf16 v[34:37], v[46:49], v[34:37], 0
	s_waitcnt lgkmcnt(1)
	v_mfma_f32_16x16x32_bf16 v[0:3], v[42:45], v[0:3], v[34:37]
	s_waitcnt lgkmcnt(0)
	v_mfma_f32_16x16x32_bf16 v[8:11], v[20:23], v[12:15], v[8:11]
	ds_read2_b64 v[20:23], v52 offset0:80 offset1:84
	s_nop 2
	ds_read2_b64 v[34:37], v53 offset0:112 offset1:116
	s_waitcnt lgkmcnt(1)
	v_mfma_f32_16x16x32_bf16 v[20:23], v[20:23], v[12:15], v[38:41]
	s_waitcnt lgkmcnt(0)
	v_mfma_f32_16x16x32_bf16 v[0:3], v[34:37], v[12:15], v[0:3]
	ds_read2_b64 v[12:15], v50 offset0:24 offset1:28
	s_waitcnt lgkmcnt(0)
	v_mfma_f32_16x16x32_bf16 v[12:15], v[12:15], v[24:27], v[4:7]
	s_nop 2
	ds_read2_b64 v[4:7], v51 offset0:56 offset1:60
	s_waitcnt vmcnt(0)
	s_nop 2
	v_pk_mul_f32 v[14:15], v[14:15], v[18:19] op_sel_hi:[1,0]
	s_waitcnt lgkmcnt(0)
	v_mfma_f32_16x16x32_bf16 v[8:11], v[4:7], v[24:27], v[8:11]
	ds_read2_b64 v[4:7], v52 offset0:88 offset1:92
	v_pk_mul_f32 v[12:13], v[12:13], v[18:19] op_sel_hi:[1,0]
	global_store_dwordx4 v[16:17], v[12:15], off
	s_waitcnt lgkmcnt(0)
	v_mfma_f32_16x16x32_bf16 v[4:7], v[4:7], v[24:27], v[20:23]
	s_nop 2
	ds_read2_b64 v[20:23], v53 offset0:120 offset1:124
	v_pk_mul_f32 v[10:11], v[10:11], v[18:19] op_sel_hi:[1,0]
	v_pk_mul_f32 v[8:9], v[8:9], v[18:19] op_sel_hi:[1,0]
	s_waitcnt lgkmcnt(0)
	v_mfma_f32_16x16x32_bf16 v[0:3], v[20:23], v[24:27], v[0:3]
	v_mul_f32_e64 v6, v6, v18
	v_mul_f32_e64 v7, v7, v18
	v_pk_mul_f32 v[4:5], v[4:5], v[18:19] op_sel_hi:[1,0]
	global_store_dwordx4 v[16:17], v[8:11], off offset:64
	s_nop 3
	v_pk_mul_f32 v[2:3], v[2:3], v[18:19] op_sel_hi:[1,0]
	v_pk_mul_f32 v[0:1], v[0:1], v[18:19] op_sel_hi:[1,0]
	global_store_dwordx4 v[16:17], v[4:7], off offset:128
	global_store_dwordx4 v[16:17], v[0:3], off offset:192
	s_barrier
	s_mov_b64 s[74:75], exec
	v_lshrrev_b32_e32 v1, 5, v149
	s_mov_b32 s76, 0
	s_mov_b32 s77, 0
.Ltk_iter:
	v_mul_u32_u24_e32 v5, 0x84, v1
	v_add_u32_e32 v5, s33, v5
	v_lshl_add_u32 v6, v214, 2, v5
	ds_read_b32 v4, v6
	ds_read2_b32 v[8:9], v5 offset0:0 offset1:1
	ds_read2_b32 v[10:11], v5 offset0:2 offset1:3
	ds_read2_b32 v[12:13], v5 offset0:4 offset1:5
	ds_read2_b32 v[14:15], v5 offset0:6 offset1:7
	ds_read2_b32 v[16:17], v5 offset0:8 offset1:9
	ds_read2_b32 v[18:19], v5 offset0:10 offset1:11
	ds_read2_b32 v[20:21], v5 offset0:12 offset1:13
	ds_read2_b32 v[22:23], v5 offset0:14 offset1:15
	v_add_u32_e32 v2, s95, v1
	v_ashrrev_i32_e32 v2, 6, v2
	v_mov_b32_e32 v3, 0
	s_waitcnt lgkmcnt(0)
	v_cmp_gt_f32_e32 vcc, v9, v4
	v_cmp_eq_f32_e64 s[0:1], v9, v4
	v_cmp_lt_u32_e64 s[2:3], 1, v214
	s_and_b64 s[0:1], s[0:1], s[2:3]
	s_or_b64 vcc, vcc, s[0:1]
	v_cmp_le_i32_e64 s[2:3], 3, v2
	s_and_b64 vcc, vcc, s[2:3]
	v_addc_co_u32_e32 v3, vcc, 0, v3, vcc
	v_cmp_gt_f32_e32 vcc, v10, v4
	v_cmp_eq_f32_e64 s[0:1], v10, v4
	v_cmp_lt_u32_e64 s[2:3], 2, v214
	s_and_b64 s[0:1], s[0:1], s[2:3]
	s_or_b64 vcc, vcc, s[0:1]
	v_cmp_le_i32_e64 s[2:3], 4, v2
	s_and_b64 vcc, vcc, s[2:3]
	v_addc_co_u32_e32 v3, vcc, 0, v3, vcc
	v_cmp_gt_f32_e32 vcc, v11, v4
	v_cmp_eq_f32_e64 s[0:1], v11, v4
	v_cmp_lt_u32_e64 s[2:3], 3, v214
	s_and_b64 s[0:1], s[0:1], s[2:3]
	s_or_b64 vcc, vcc, s[0:1]
	v_cmp_le_i32_e64 s[2:3], 5, v2
	s_and_b64 vcc, vcc, s[2:3]
	v_addc_co_u32_e32 v3, vcc, 0, v3, vcc
	v_cmp_gt_f32_e32 vcc, v12, v4
	v_cmp_eq_f32_e64 s[0:1], v12, v4
	v_cmp_lt_u32_e64 s[2:3], 4, v214
	s_and_b64 s[0:1], s[0:1], s[2:3]
	s_or_b64 vcc, vcc, s[0:1]
	v_cmp_le_i32_e64 s[2:3], 6, v2
	s_and_b64 vcc, vcc, s[2:3]
	v_addc_co_u32_e32 v3, vcc, 0, v3, vcc
	v_cmp_gt_f32_e32 vcc, v13, v4
	v_cmp_eq_f32_e64 s[0:1], v13, v4
	v_cmp_lt_u32_e64 s[2:3], 5, v214
	s_and_b64 s[0:1], s[0:1], s[2:3]
	s_or_b64 vcc, vcc, s[0:1]
	v_cmp_le_i32_e64 s[2:3], 7, v2
	s_and_b64 vcc, vcc, s[2:3]
	v_addc_co_u32_e32 v3, vcc, 0, v3, vcc
	v_cmp_gt_f32_e32 vcc, v14, v4
	v_cmp_eq_f32_e64 s[0:1], v14, v4
	v_cmp_lt_u32_e64 s[2:3], 6, v214
	s_and_b64 s[0:1], s[0:1], s[2:3]
	s_or_b64 vcc, vcc, s[0:1]
	v_cmp_le_i32_e64 s[2:3], 8, v2
	s_and_b64 vcc, vcc, s[2:3]
	v_addc_co_u32_e32 v3, vcc, 0, v3, vcc
	v_cmp_gt_f32_e32 vcc, v15, v4
	v_cmp_eq_f32_e64 s[0:1], v15, v4
	v_cmp_lt_u32_e64 s[2:3], 7, v214
	s_and_b64 s[0:1], s[0:1], s[2:3]
	s_or_b64 vcc, vcc, s[0:1]
	v_cmp_le_i32_e64 s[2:3], 9, v2
	s_and_b64 vcc, vcc, s[2:3]
	v_addc_co_u32_e32 v3, vcc, 0, v3, vcc
	v_cmp_gt_f32_e32 vcc, v16, v4
	v_cmp_eq_f32_e64 s[0:1], v16, v4
	v_cmp_lt_u32_e64 s[2:3], 8, v214
	s_and_b64 s[0:1], s[0:1], s[2:3]
	s_or_b64 vcc, vcc, s[0:1]
	v_cmp_le_i32_e64 s[2:3], 10, v2
	s_and_b64 vcc, vcc, s[2:3]
	v_addc_co_u32_e32 v3, vcc, 0, v3, vcc
	v_cmp_gt_f32_e32 vcc, v17, v4
	v_cmp_eq_f32_e64 s[0:1], v17, v4
	v_cmp_lt_u32_e64 s[2:3], 9, v214
	s_and_b64 s[0:1], s[0:1], s[2:3]
	s_or_b64 vcc, vcc, s[0:1]
	v_cmp_le_i32_e64 s[2:3], 11, v2
	s_and_b64 vcc, vcc, s[2:3]
	v_addc_co_u32_e32 v3, vcc, 0, v3, vcc
	v_cmp_gt_f32_e32 vcc, v18, v4
	v_cmp_eq_f32_e64 s[0:1], v18, v4
	v_cmp_lt_u32_e64 s[2:3], 10, v214
	s_and_b64 s[0:1], s[0:1], s[2:3]
	s_or_b64 vcc, vcc, s[0:1]
	v_cmp_le_i32_e64 s[2:3], 12, v2
	s_and_b64 vcc, vcc, s[2:3]
	v_addc_co_u32_e32 v3, vcc, 0, v3, vcc
	v_cmp_gt_f32_e32 vcc, v19, v4
	v_cmp_eq_f32_e64 s[0:1], v19, v4
	v_cmp_lt_u32_e64 s[2:3], 11, v214
	s_and_b64 s[0:1], s[0:1], s[2:3]
	s_or_b64 vcc, vcc, s[0:1]
	v_cmp_le_i32_e64 s[2:3], 13, v2
	s_and_b64 vcc, vcc, s[2:3]
	v_addc_co_u32_e32 v3, vcc, 0, v3, vcc
	v_cmp_gt_f32_e32 vcc, v20, v4
	v_cmp_eq_f32_e64 s[0:1], v20, v4
	v_cmp_lt_u32_e64 s[2:3], 12, v214
	s_and_b64 s[0:1], s[0:1], s[2:3]
	s_or_b64 vcc, vcc, s[0:1]
	v_cmp_le_i32_e64 s[2:3], 14, v2
	s_and_b64 vcc, vcc, s[2:3]
	v_addc_co_u32_e32 v3, vcc, 0, v3, vcc
	v_cmp_gt_f32_e32 vcc, v21, v4
	v_cmp_eq_f32_e64 s[0:1], v21, v4
	v_cmp_lt_u32_e64 s[2:3], 13, v214
	s_and_b64 s[0:1], s[0:1], s[2:3]
	s_or_b64 vcc, vcc, s[0:1]
	v_cmp_le_i32_e64 s[2:3], 15, v2
	s_and_b64 vcc, vcc, s[2:3]
	v_addc_co_u32_e32 v3, vcc, 0, v3, vcc
	v_cmp_gt_f32_e32 vcc, v22, v4
	v_cmp_eq_f32_e64 s[0:1], v22, v4
	v_cmp_lt_u32_e64 s[2:3], 14, v214
	s_and_b64 s[0:1], s[0:1], s[2:3]
	s_or_b64 vcc, vcc, s[0:1]
	v_cmp_le_i32_e64 s[2:3], 16, v2
	s_and_b64 vcc, vcc, s[2:3]
	v_addc_co_u32_e32 v3, vcc, 0, v3, vcc
	v_cmp_gt_f32_e32 vcc, v23, v4
	v_cmp_eq_f32_e64 s[0:1], v23, v4
	v_cmp_lt_u32_e64 s[2:3], 15, v214
	s_and_b64 s[0:1], s[0:1], s[2:3]
	s_or_b64 vcc, vcc, s[0:1]
	v_cmp_le_i32_e64 s[2:3], 17, v2
	s_and_b64 vcc, vcc, s[2:3]
	v_addc_co_u32_e32 v3, vcc, 0, v3, vcc
	ds_read2_b32 v[8:9], v5 offset0:16 offset1:17
	ds_read2_b32 v[10:11], v5 offset0:18 offset1:19
	ds_read2_b32 v[12:13], v5 offset0:20 offset1:21
	ds_read2_b32 v[14:15], v5 offset0:22 offset1:23
	ds_read2_b32 v[16:17], v5 offset0:24 offset1:25
	ds_read2_b32 v[18:19], v5 offset0:26 offset1:27
	ds_read2_b32 v[20:21], v5 offset0:28 offset1:29
	ds_read2_b32 v[22:23], v5 offset0:30 offset1:31
	s_waitcnt lgkmcnt(0)
	v_cmp_gt_f32_e32 vcc, v8, v4
	v_cmp_eq_f32_e64 s[0:1], v8, v4
	v_cmp_lt_u32_e64 s[2:3], 16, v214
	s_and_b64 s[0:1], s[0:1], s[2:3]
	s_or_b64 vcc, vcc, s[0:1]
	v_cmp_le_i32_e64 s[2:3], 18, v2
	s_and_b64 vcc, vcc, s[2:3]
	v_addc_co_u32_e32 v3, vcc, 0, v3, vcc
	v_cmp_gt_f32_e32 vcc, v9, v4
	v_cmp_eq_f32_e64 s[0:1], v9, v4
	v_cmp_lt_u32_e64 s[2:3], 17, v214
	s_and_b64 s[0:1], s[0:1], s[2:3]
	s_or_b64 vcc, vcc, s[0:1]
	v_cmp_le_i32_e64 s[2:3], 19, v2
	s_and_b64 vcc, vcc, s[2:3]
	v_addc_co_u32_e32 v3, vcc, 0, v3, vcc
	v_cmp_gt_f32_e32 vcc, v10, v4
	v_cmp_eq_f32_e64 s[0:1], v10, v4
	v_cmp_lt_u32_e64 s[2:3], 18, v214
	s_and_b64 s[0:1], s[0:1], s[2:3]
	s_or_b64 vcc, vcc, s[0:1]
	v_cmp_le_i32_e64 s[2:3], 20, v2
	s_and_b64 vcc, vcc, s[2:3]
	v_addc_co_u32_e32 v3, vcc, 0, v3, vcc
	v_cmp_gt_f32_e32 vcc, v11, v4
	v_cmp_eq_f32_e64 s[0:1], v11, v4
	v_cmp_lt_u32_e64 s[2:3], 19, v214
	s_and_b64 s[0:1], s[0:1], s[2:3]
	s_or_b64 vcc, vcc, s[0:1]
	v_cmp_le_i32_e64 s[2:3], 21, v2
	s_and_b64 vcc, vcc, s[2:3]
	v_addc_co_u32_e32 v3, vcc, 0, v3, vcc
	v_cmp_gt_f32_e32 vcc, v12, v4
	v_cmp_eq_f32_e64 s[0:1], v12, v4
	v_cmp_lt_u32_e64 s[2:3], 20, v214
	s_and_b64 s[0:1], s[0:1], s[2:3]
	s_or_b64 vcc, vcc, s[0:1]
	v_cmp_le_i32_e64 s[2:3], 22, v2
	s_and_b64 vcc, vcc, s[2:3]
	v_addc_co_u32_e32 v3, vcc, 0, v3, vcc
	v_cmp_gt_f32_e32 vcc, v13, v4
	v_cmp_eq_f32_e64 s[0:1], v13, v4
	v_cmp_lt_u32_e64 s[2:3], 21, v214
	s_and_b64 s[0:1], s[0:1], s[2:3]
	s_or_b64 vcc, vcc, s[0:1]
	v_cmp_le_i32_e64 s[2:3], 23, v2
	s_and_b64 vcc, vcc, s[2:3]
	v_addc_co_u32_e32 v3, vcc, 0, v3, vcc
	v_cmp_gt_f32_e32 vcc, v14, v4
	v_cmp_eq_f32_e64 s[0:1], v14, v4
	v_cmp_lt_u32_e64 s[2:3], 22, v214
	s_and_b64 s[0:1], s[0:1], s[2:3]
	s_or_b64 vcc, vcc, s[0:1]
	v_cmp_le_i32_e64 s[2:3], 24, v2
	s_and_b64 vcc, vcc, s[2:3]
	v_addc_co_u32_e32 v3, vcc, 0, v3, vcc
	v_cmp_gt_f32_e32 vcc, v15, v4
	v_cmp_eq_f32_e64 s[0:1], v15, v4
	v_cmp_lt_u32_e64 s[2:3], 23, v214
	s_and_b64 s[0:1], s[0:1], s[2:3]
	s_or_b64 vcc, vcc, s[0:1]
	v_cmp_le_i32_e64 s[2:3], 25, v2
	s_and_b64 vcc, vcc, s[2:3]
	v_addc_co_u32_e32 v3, vcc, 0, v3, vcc
	v_cmp_gt_f32_e32 vcc, v16, v4
	v_cmp_eq_f32_e64 s[0:1], v16, v4
	v_cmp_lt_u32_e64 s[2:3], 24, v214
	s_and_b64 s[0:1], s[0:1], s[2:3]
	s_or_b64 vcc, vcc, s[0:1]
	v_cmp_le_i32_e64 s[2:3], 26, v2
	s_and_b64 vcc, vcc, s[2:3]
	v_addc_co_u32_e32 v3, vcc, 0, v3, vcc
	v_cmp_gt_f32_e32 vcc, v17, v4
	v_cmp_eq_f32_e64 s[0:1], v17, v4
	v_cmp_lt_u32_e64 s[2:3], 25, v214
	s_and_b64 s[0:1], s[0:1], s[2:3]
	s_or_b64 vcc, vcc, s[0:1]
	v_cmp_le_i32_e64 s[2:3], 27, v2
	s_and_b64 vcc, vcc, s[2:3]
	v_addc_co_u32_e32 v3, vcc, 0, v3, vcc
	v_cmp_gt_f32_e32 vcc, v18, v4
	v_cmp_eq_f32_e64 s[0:1], v18, v4
	v_cmp_lt_u32_e64 s[2:3], 26, v214
	s_and_b64 s[0:1], s[0:1], s[2:3]
	s_or_b64 vcc, vcc, s[0:1]
	v_cmp_le_i32_e64 s[2:3], 28, v2
	s_and_b64 vcc, vcc, s[2:3]
	v_addc_co_u32_e32 v3, vcc, 0, v3, vcc
	v_cmp_gt_f32_e32 vcc, v19, v4
	v_cmp_eq_f32_e64 s[0:1], v19, v4
	v_cmp_lt_u32_e64 s[2:3], 27, v214
	s_and_b64 s[0:1], s[0:1], s[2:3]
	s_or_b64 vcc, vcc, s[0:1]
	v_cmp_le_i32_e64 s[2:3], 29, v2
	s_and_b64 vcc, vcc, s[2:3]
	v_addc_co_u32_e32 v3, vcc, 0, v3, vcc
	v_cmp_gt_f32_e32 vcc, v20, v4
	v_cmp_eq_f32_e64 s[0:1], v20, v4
	v_cmp_lt_u32_e64 s[2:3], 28, v214
	s_and_b64 s[0:1], s[0:1], s[2:3]
	s_or_b64 vcc, vcc, s[0:1]
	v_cmp_le_i32_e64 s[2:3], 30, v2
	s_and_b64 vcc, vcc, s[2:3]
	v_addc_co_u32_e32 v3, vcc, 0, v3, vcc
	v_cmp_gt_f32_e32 vcc, v21, v4
	v_cmp_eq_f32_e64 s[0:1], v21, v4
	v_cmp_lt_u32_e64 s[2:3], 29, v214
	s_and_b64 s[0:1], s[0:1], s[2:3]
	s_or_b64 vcc, vcc, s[0:1]
	v_cmp_le_i32_e64 s[2:3], 31, v2
	s_and_b64 vcc, vcc, s[2:3]
	v_addc_co_u32_e32 v3, vcc, 0, v3, vcc
	v_cmp_le_i32_e64 s[0:1], v214, v2
	v_cmp_eq_u32_e64 s[2:3], v214, v2
	v_add_u32_e32 v6, -1, v2
	s_or_b64 s[2:3], s[2:3], s[8:9]
	v_cmp_eq_u32_e32 vcc, v214, v6
	s_or_b64 s[2:3], s[2:3], vcc
	v_cmp_gt_u32_e32 vcc, 8, v2
	s_or_b64 s[4:5], s[2:3], vcc
	v_cmp_gt_u32_e32 vcc, 5, v3
	s_andn2_b64 vcc, vcc, s[2:3]
	s_or_b64 s[4:5], s[4:5], vcc
	s_and_b64 s[4:5], s[4:5], s[0:1]
	v_mov_b32_e32 v6, s5
	v_mov_b32_e32 v7, s4
	v_cndmask_b32_e64 v6, v6, v7, s[10:11]
	v_lshlrev_b32_e32 v7, 2, v1
	v_add_u32_e32 v7, 0x1ac00, v7
	s_and_saveexec_b64 s[2:3], s[8:9]
	ds_write_b32 v7, v6
	s_mov_b64 exec, s[2:3]
	s_or_b32 s76, s76, s4
	s_or_b32 s76, s76, s5
	v_add_u32_e32 v1, 16, v1
	s_add_u32 s77, s77, 1
	s_cmp_lt_u32 s77, 2
	s_cbranch_scc1 .Ltk_iter
	v_readlane_b32 s0, v251, 27
	v_mov_b32_e32 v6, s76
	s_nop 1
	v_mov_b32_e32 v7, s0
	s_and_saveexec_b64 s[2:3], s[10:11]
	ds_or_b32 v7, v6
	s_mov_b64 exec, s[2:3]

.LBB0_1965:
	s_waitcnt vmcnt(0)
	s_ff1_i32_b32 s22, s23
	s_lshl_b32 s12, s22, 6
	s_and_saveexec_b64 s[2:3], s[4:5]
	s_cbranch_execz .LBB0_1967
	v_add_u32_e32 v0, s12, v185
	v_mad_i64_i32 v[0:1], s[24:25], v0, s85, v[166:167]
	global_load_dwordx4 v[0:3], v[0:1], off
.LBB0_1967:
	s_or_b64 exec, exec, s[2:3]
	s_and_saveexec_b64 s[2:3], s[6:7]
	s_cbranch_execz .LBB0_1969
	v_add_u32_e32 v4, s12, v181
	v_mad_i64_i32 v[4:5], s[24:25], v4, s85, v[168:169]
	global_load_dwordx4 v[4:7], v[4:5], off
.LBB0_1969:
	s_or_b64 exec, exec, s[2:3]
	s_lshl_b32 s96, s12, 1
	v_lshl_add_u64 v[56:57], v[164:165], 0, s[96:97]
	global_load_dwordx4 v[56:59], v[56:57], off
	s_add_i32 s2, s23, -1
	s_and_b32 s12, s2, s23
	s_cmp_eq_u32 s12, 0
	s_mov_b32 s23, 0
	s_cbranch_scc1 .LBB0_1964
.LBB0_1970:
	s_ff1_i32_b32 s24, s12
	s_lshl_b32 s13, s24, 6
	s_and_saveexec_b64 s[2:3], s[4:5]
	s_cbranch_execz .LBB0_1972
	v_add_u32_e32 v8, s13, v185
	v_mad_i64_i32 v[8:9], s[26:27], v8, s85, v[166:167]
	global_load_dwordx4 v[8:11], v[8:9], off
.LBB0_1972:
	s_or_b64 exec, exec, s[2:3]
	s_and_saveexec_b64 s[2:3], s[6:7]
	s_cbranch_execz .LBB0_1974
	v_add_u32_e32 v12, s13, v181
	v_mad_i64_i32 v[12:13], s[26:27], v12, s85, v[168:169]
	global_load_dwordx4 v[12:15], v[12:13], off
.LBB0_1974:
	s_or_b64 exec, exec, s[2:3]
	s_lshl_b32 s96, s13, 1
	v_lshl_add_u64 v[60:61], v[164:165], 0, s[96:97]
	global_load_dwordx4 v[60:63], v[60:61], off
	s_add_i32 s2, s12, -1
	s_and_b32 s23, s2, s12
